# prologue w_in tiles by the hand-written prefetching transposer (x pointers parked in v238 lanes)
# baseline (speedup 1.0000x reference)
.LBB0_47:
	s_andn2_b64 vcc, exec, s[0:1]
	s_cbranch_vccnz .LBB0_63
	v_readlane_b32 s0, v241, 0
	s_cmpk_gt_i32 s0, 0x18bf
	s_cbranch_scc1 .LBB0_63
	v_mov_b32_e32 v9, 0
	s_add_u32 s0, s92, 0xc700000
	s_brev_b32 s8, 63
	v_lshlrev_b32_e32 v6, 3, v178
	v_mov_b32_e32 v7, v9
	s_addc_u32 s1, s93, 0
	s_mov_b32 s5, 0
	s_mov_b64 s[6:7], 0x1000000
	s_mov_b32 s9, -1
	s_movk_i32 s11, 0xfff
	s_movk_i32 s52, 0x1a08
	s_movk_i32 s53, 0x1a18
	s_movk_i32 s54, 0x6860
	s_mov_b32 s10, 0x3d800000
	s_movk_i32 s55, 0x204
	v_readlane_b32 s56, v241, 0
	v_writelane_b32 v238, s12, 60
	v_writelane_b32 v238, s13, 61
	v_writelane_b32 v238, s14, 62
	v_writelane_b32 v238, s15, 63
	s_mov_b32 s8, 0
	s_mov_b32 s14, s92
	s_mov_b32 s15, s93
	v_lshrrev_b32_e32 v117, 5, v178
	v_and_b32_e32 v168, 31, v178
	v_lshlrev_b32_e32 v116, 2, v168
	v_mul_u32_u24_e32 v16, 0x204, v117
	v_lshl_add_u32 v16, v116, 2, v16
	v_and_b32_e32 v168, 7, v178
	v_lshlrev_b32_e32 v120, 4, v168
	v_mul_u32_u24_e32 v17, 0x1020, v168
	v_lshrrev_b32_e32 v119, 3, v178
	v_lshl_add_u32 v17, v119, 2, v17
	s_add_i32 s4, s56, 0
	s_mov_b32 s39, 0
	s_cmpk_lt_u32 s4, 0x6c0
	s_cbranch_scc0 .Ltrpro_t1_0
	s_lshr_b32 s5, s4, 5
	s_and_b32 s6, s4, 31
	v_readlane_b32 s28, v241, 11
	v_readlane_b32 s29, v241, 12
	s_mul_i32 s9, s8, 0x3430000
	s_movk_i32 s38, 0x6860
	s_mov_b32 s2, 0
	s_mul_i32 s3, s8, 0x1b00000
	s_movk_i32 s44, 0x1000
	s_mov_b32 s39, 1
	s_branch .Ltrpro_dec_0

.Ltrpro_nosc:
	v_mov_b32_e32 v168, v16
	ds_write2_b32 v168, v100, v101 offset1:1
	ds_write2_b32 v168, v102, v103 offset0:2 offset1:3
	v_add_u32_e32 v168, 8256, v16
	ds_write2_b32 v168, v104, v105 offset1:1
	ds_write2_b32 v168, v106, v107 offset0:2 offset1:3
	v_add_u32_e32 v168, 16512, v16
	ds_write2_b32 v168, v108, v109 offset1:1
	ds_write2_b32 v168, v110, v111 offset0:2 offset1:3
	v_add_u32_e32 v168, 24768, v16
	ds_write2_b32 v168, v112, v113 offset1:1
	ds_write2_b32 v168, v114, v115 offset0:2 offset1:3
	s_add_i32 s56, s56, 256
	s_cmpk_lt_u32 s56, 0x6c0
	s_cselect_b32 s7, 1, 0
	s_cbranch_scc0 .Ltrpro_nonext
	s_add_i32 s4, s56, 0
	s_mov_b32 s39, 0
	s_cmpk_lt_u32 s4, 0x6c0
	s_cbranch_scc0 .Ltrpro_t1_1
	s_lshr_b32 s5, s4, 5
	s_and_b32 s6, s4, 31
	v_readlane_b32 s28, v241, 11
	v_readlane_b32 s29, v241, 12
	s_mul_i32 s9, s8, 0x3430000
	s_movk_i32 s38, 0x6860
	s_mov_b32 s2, 0
	s_mul_i32 s3, s8, 0x1b00000
	s_movk_i32 s44, 0x1000
	s_mov_b32 s39, 1
	s_branch .Ltrpro_dec_1

.Lpro_done:
	v_readlane_b32 s12, v238, 60
	v_readlane_b32 s13, v238, 61
	v_readlane_b32 s14, v238, 62
	v_readlane_b32 s15, v238, 63
	s_nop 1
	s_branch .LBB0_52

.LBB0_54:
	v_lshlrev_b32_e32 v10, 5, v178
	v_lshlrev_b32_e32 v11, 4, v178
	s_add_i32 s4, s56, -1728
	s_cmpk_lt_u32 s4, 0x1000
	s_cselect_b32 s34, s12, s14
	s_cselect_b32 s35, s13, s15
	s_cselect_b32 s2, 0, 0x1000
	s_sub_i32 s2, s4, s2
	s_lshl_b32 s2, s2, 14
	s_add_u32 s34, s34, s2
	s_addc_u32 s35, s35, 0
	s_lshl_b32 s2, s4, 13
	s_add_u32 s36, s0, s2
	s_addc_u32 s37, s1, 0
	global_load_dwordx4 v[0:3], v10, s[34:35]
	global_load_dwordx4 v[12:15], v10, s[34:35] offset:16
	s_add_i32 s4, s56, -1472
	s_cmpk_lt_u32 s4, 0x1000
	s_cselect_b32 s34, s12, s14
	s_cselect_b32 s35, s13, s15
	s_cselect_b32 s2, 0, 0x1000
	s_sub_i32 s2, s4, s2
	s_lshl_b32 s2, s2, 14
	s_add_u32 s34, s34, s2
	s_addc_u32 s35, s35, 0
	s_lshl_b32 s2, s4, 13
	s_add_u32 s38, s0, s2
	s_addc_u32 s39, s1, 0
	global_load_dwordx4 v[16:19], v10, s[34:35]
	global_load_dwordx4 v[20:23], v10, s[34:35] offset:16
	s_add_i32 s4, s56, -1216
	s_cmpk_lt_u32 s4, 0x1000
	s_cselect_b32 s34, s12, s14
	s_cselect_b32 s35, s13, s15
	s_cselect_b32 s2, 0, 0x1000
	s_sub_i32 s2, s4, s2
	s_lshl_b32 s2, s2, 14
	s_add_u32 s34, s34, s2
	s_addc_u32 s35, s35, 0
	s_lshl_b32 s2, s4, 13
	s_add_u32 s40, s0, s2
	s_addc_u32 s41, s1, 0
	global_load_dwordx4 v[24:27], v10, s[34:35]
	global_load_dwordx4 v[244:247], v10, s[34:35] offset:16
	s_add_i32 s4, s56, -960
	s_cmpk_lt_u32 s4, 0x1000
	s_cselect_b32 s34, s12, s14
	s_cselect_b32 s35, s13, s15
	s_cselect_b32 s2, 0, 0x1000
	s_sub_i32 s2, s4, s2
	s_lshl_b32 s2, s2, 14
	s_add_u32 s34, s34, s2
	s_addc_u32 s35, s35, 0
	s_lshl_b32 s2, s4, 13
	s_add_u32 s42, s0, s2
	s_addc_u32 s43, s1, 0
	global_load_dwordx4 v[248:251], v10, s[34:35]
	global_load_dwordx4 v[252:255], v10, s[34:35] offset:16
	s_waitcnt vmcnt(4)
	v_cvt_pk_bf16_f32 v0, v0, v1
	v_cvt_pk_bf16_f32 v1, v2, v3
	v_cvt_pk_bf16_f32 v2, v12, v13
	v_cvt_pk_bf16_f32 v3, v14, v15
	global_store_dwordx4 v11, v[0:3], s[36:37]
	v_cvt_pk_bf16_f32 v16, v16, v17
	v_cvt_pk_bf16_f32 v17, v18, v19
	v_cvt_pk_bf16_f32 v18, v20, v21
	v_cvt_pk_bf16_f32 v19, v22, v23
	global_store_dwordx4 v11, v[16:19], s[38:39]
	s_nop 1
	s_add_i32 s4, s56, -704
	s_cmpk_lt_u32 s4, 0x1000
	s_cselect_b32 s34, s12, s14
	s_cselect_b32 s35, s13, s15
	s_cselect_b32 s2, 0, 0x1000
	s_sub_i32 s2, s4, s2
	s_lshl_b32 s2, s2, 14
	s_add_u32 s34, s34, s2
	s_addc_u32 s35, s35, 0
	s_lshl_b32 s2, s4, 13
	s_add_u32 s36, s0, s2
	s_addc_u32 s37, s1, 0
	global_load_dwordx4 v[0:3], v10, s[34:35]
	global_load_dwordx4 v[12:15], v10, s[34:35] offset:16
	s_add_i32 s4, s56, -448
	s_cmpk_lt_u32 s4, 0x1000
	s_cselect_b32 s34, s12, s14
	s_cselect_b32 s35, s13, s15
	s_cselect_b32 s2, 0, 0x1000
	s_sub_i32 s2, s4, s2
	s_lshl_b32 s2, s2, 14
	s_add_u32 s34, s34, s2
	s_addc_u32 s35, s35, 0
	s_lshl_b32 s2, s4, 13
	s_add_u32 s38, s0, s2
	s_addc_u32 s39, s1, 0
	global_load_dwordx4 v[16:19], v10, s[34:35]
	global_load_dwordx4 v[20:23], v10, s[34:35] offset:16
	s_waitcnt vmcnt(6)
	v_cvt_pk_bf16_f32 v24, v24, v25
	v_cvt_pk_bf16_f32 v25, v26, v27
	v_cvt_pk_bf16_f32 v26, v244, v245
	v_cvt_pk_bf16_f32 v27, v246, v247
	global_store_dwordx4 v11, v[24:27], s[40:41]
	v_cvt_pk_bf16_f32 v248, v248, v249
	v_cvt_pk_bf16_f32 v249, v250, v251
	v_cvt_pk_bf16_f32 v250, v252, v253
	v_cvt_pk_bf16_f32 v251, v254, v255
	global_store_dwordx4 v11, v[248:251], s[42:43]
	s_nop 1
	s_add_i32 s4, s56, -192
	s_cmpk_lt_u32 s4, 0x1000
	s_cselect_b32 s34, s12, s14
	s_cselect_b32 s35, s13, s15
	s_cselect_b32 s2, 0, 0x1000
	s_sub_i32 s2, s4, s2
	s_lshl_b32 s2, s2, 14
	s_add_u32 s34, s34, s2
	s_addc_u32 s35, s35, 0
	s_lshl_b32 s2, s4, 13
	s_add_u32 s40, s0, s2
	s_addc_u32 s41, s1, 0
	global_load_dwordx4 v[24:27], v10, s[34:35]
	global_load_dwordx4 v[244:247], v10, s[34:35] offset:16
	s_add_i32 s4, s56, 64
	s_cmpk_lt_u32 s4, 0x1000
	s_cselect_b32 s34, s12, s14
	s_cselect_b32 s35, s13, s15
	s_cselect_b32 s2, 0, 0x1000
	s_sub_i32 s2, s4, s2
	s_lshl_b32 s2, s2, 14
	s_add_u32 s34, s34, s2
	s_addc_u32 s35, s35, 0
	s_lshl_b32 s2, s4, 13
	s_add_u32 s42, s0, s2
	s_addc_u32 s43, s1, 0
	global_load_dwordx4 v[248:251], v10, s[34:35]
	global_load_dwordx4 v[252:255], v10, s[34:35] offset:16
	s_waitcnt vmcnt(6)
	v_cvt_pk_bf16_f32 v0, v0, v1
	v_cvt_pk_bf16_f32 v1, v2, v3
	v_cvt_pk_bf16_f32 v2, v12, v13
	v_cvt_pk_bf16_f32 v3, v14, v15
	global_store_dwordx4 v11, v[0:3], s[36:37]
	v_cvt_pk_bf16_f32 v16, v16, v17
	v_cvt_pk_bf16_f32 v17, v18, v19
	v_cvt_pk_bf16_f32 v18, v20, v21
	v_cvt_pk_bf16_f32 v19, v22, v23
	global_store_dwordx4 v11, v[16:19], s[38:39]
	s_nop 1
	s_add_i32 s4, s56, 320
	s_cmpk_lt_u32 s4, 0x1000
	s_cselect_b32 s34, s12, s14
	s_cselect_b32 s35, s13, s15
	s_cselect_b32 s2, 0, 0x1000
	s_sub_i32 s2, s4, s2
	s_lshl_b32 s2, s2, 14
	s_add_u32 s34, s34, s2
	s_addc_u32 s35, s35, 0
	s_lshl_b32 s2, s4, 13
	s_add_u32 s36, s0, s2
	s_addc_u32 s37, s1, 0
	global_load_dwordx4 v[0:3], v10, s[34:35]
	global_load_dwordx4 v[12:15], v10, s[34:35] offset:16
	s_add_i32 s4, s56, 576
	s_cmpk_lt_u32 s4, 0x1000
	s_cselect_b32 s34, s12, s14
	s_cselect_b32 s35, s13, s15
	s_cselect_b32 s2, 0, 0x1000
	s_sub_i32 s2, s4, s2
	s_lshl_b32 s2, s2, 14
	s_add_u32 s34, s34, s2
	s_addc_u32 s35, s35, 0
	s_lshl_b32 s2, s4, 13
	s_add_u32 s38, s0, s2
	s_addc_u32 s39, s1, 0
	global_load_dwordx4 v[16:19], v10, s[34:35]
	global_load_dwordx4 v[20:23], v10, s[34:35] offset:16
	s_waitcnt vmcnt(6)
	v_cvt_pk_bf16_f32 v24, v24, v25
	v_cvt_pk_bf16_f32 v25, v26, v27
	v_cvt_pk_bf16_f32 v26, v244, v245
	v_cvt_pk_bf16_f32 v27, v246, v247
	global_store_dwordx4 v11, v[24:27], s[40:41]
	v_cvt_pk_bf16_f32 v248, v248, v249
	v_cvt_pk_bf16_f32 v249, v250, v251
	v_cvt_pk_bf16_f32 v250, v252, v253
	v_cvt_pk_bf16_f32 v251, v254, v255
	global_store_dwordx4 v11, v[248:251], s[42:43]
	s_nop 1
	s_add_i32 s4, s56, 832
	s_cmpk_lt_u32 s4, 0x1000
	s_cselect_b32 s34, s12, s14
	s_cselect_b32 s35, s13, s15
	s_cselect_b32 s2, 0, 0x1000
	s_sub_i32 s2, s4, s2
	s_lshl_b32 s2, s2, 14
	s_add_u32 s34, s34, s2
	s_addc_u32 s35, s35, 0
	s_lshl_b32 s2, s4, 13
	s_add_u32 s40, s0, s2
	s_addc_u32 s41, s1, 0
	global_load_dwordx4 v[24:27], v10, s[34:35]
	global_load_dwordx4 v[244:247], v10, s[34:35] offset:16
	s_add_i32 s4, s56, 1088
	s_cmpk_lt_u32 s4, 0x1000
	s_cselect_b32 s34, s12, s14
	s_cselect_b32 s35, s13, s15
	s_cselect_b32 s2, 0, 0x1000
	s_sub_i32 s2, s4, s2
	s_lshl_b32 s2, s2, 14
	s_add_u32 s34, s34, s2
	s_addc_u32 s35, s35, 0
	s_lshl_b32 s2, s4, 13
	s_add_u32 s42, s0, s2
	s_addc_u32 s43, s1, 0
	global_load_dwordx4 v[248:251], v10, s[34:35]
	global_load_dwordx4 v[252:255], v10, s[34:35] offset:16
	s_waitcnt vmcnt(6)
	v_cvt_pk_bf16_f32 v0, v0, v1
	v_cvt_pk_bf16_f32 v1, v2, v3
	v_cvt_pk_bf16_f32 v2, v12, v13
	v_cvt_pk_bf16_f32 v3, v14, v15
	global_store_dwordx4 v11, v[0:3], s[36:37]
	v_cvt_pk_bf16_f32 v16, v16, v17
	v_cvt_pk_bf16_f32 v17, v18, v19
	v_cvt_pk_bf16_f32 v18, v20, v21
	v_cvt_pk_bf16_f32 v19, v22, v23
	global_store_dwordx4 v11, v[16:19], s[38:39]
	s_nop 1
	s_add_i32 s4, s56, 1344
	s_cmpk_lt_u32 s4, 0x1000
	s_cselect_b32 s34, s12, s14
	s_cselect_b32 s35, s13, s15
	s_cselect_b32 s2, 0, 0x1000
	s_sub_i32 s2, s4, s2
	s_lshl_b32 s2, s2, 14
	s_add_u32 s34, s34, s2
	s_addc_u32 s35, s35, 0
	s_lshl_b32 s2, s4, 13
	s_add_u32 s36, s0, s2
	s_addc_u32 s37, s1, 0
	global_load_dwordx4 v[0:3], v10, s[34:35]
	global_load_dwordx4 v[12:15], v10, s[34:35] offset:16
	s_add_i32 s4, s56, 1600
	s_cmpk_lt_u32 s4, 0x1000
	s_cselect_b32 s34, s12, s14
	s_cselect_b32 s35, s13, s15
	s_cselect_b32 s2, 0, 0x1000
	s_sub_i32 s2, s4, s2
	s_lshl_b32 s2, s2, 14
	s_add_u32 s34, s34, s2
	s_addc_u32 s35, s35, 0
	s_lshl_b32 s2, s4, 13
	s_add_u32 s38, s0, s2
	s_addc_u32 s39, s1, 0
	global_load_dwordx4 v[16:19], v10, s[34:35]
	global_load_dwordx4 v[20:23], v10, s[34:35] offset:16
	s_waitcnt vmcnt(6)
	v_cvt_pk_bf16_f32 v24, v24, v25
	v_cvt_pk_bf16_f32 v25, v26, v27
	v_cvt_pk_bf16_f32 v26, v244, v245
	v_cvt_pk_bf16_f32 v27, v246, v247
	global_store_dwordx4 v11, v[24:27], s[40:41]
	v_cvt_pk_bf16_f32 v248, v248, v249
	v_cvt_pk_bf16_f32 v249, v250, v251
	v_cvt_pk_bf16_f32 v250, v252, v253
	v_cvt_pk_bf16_f32 v251, v254, v255
	global_store_dwordx4 v11, v[248:251], s[42:43]
	s_nop 1
	s_add_i32 s4, s56, 1856
	s_cmpk_lt_u32 s4, 0x1000
	s_cselect_b32 s34, s12, s14
	s_cselect_b32 s35, s13, s15
	s_cselect_b32 s2, 0, 0x1000
	s_sub_i32 s2, s4, s2
	s_lshl_b32 s2, s2, 14
	s_add_u32 s34, s34, s2
	s_addc_u32 s35, s35, 0
	s_lshl_b32 s2, s4, 13
	s_add_u32 s40, s0, s2
	s_addc_u32 s41, s1, 0
	global_load_dwordx4 v[24:27], v10, s[34:35]
	global_load_dwordx4 v[244:247], v10, s[34:35] offset:16
	s_add_i32 s4, s56, 2112
	s_cmpk_lt_u32 s4, 0x1000
	s_cselect_b32 s34, s12, s14
	s_cselect_b32 s35, s13, s15
	s_cselect_b32 s2, 0, 0x1000
	s_sub_i32 s2, s4, s2
	s_lshl_b32 s2, s2, 14
	s_add_u32 s34, s34, s2
	s_addc_u32 s35, s35, 0
	s_lshl_b32 s2, s4, 13
	s_add_u32 s42, s0, s2
	s_addc_u32 s43, s1, 0
	global_load_dwordx4 v[248:251], v10, s[34:35]
	global_load_dwordx4 v[252:255], v10, s[34:35] offset:16
	s_waitcnt vmcnt(6)
	v_cvt_pk_bf16_f32 v0, v0, v1
	v_cvt_pk_bf16_f32 v1, v2, v3
	v_cvt_pk_bf16_f32 v2, v12, v13
	v_cvt_pk_bf16_f32 v3, v14, v15
	global_store_dwordx4 v11, v[0:3], s[36:37]
	v_cvt_pk_bf16_f32 v16, v16, v17
	v_cvt_pk_bf16_f32 v17, v18, v19
	v_cvt_pk_bf16_f32 v18, v20, v21
	v_cvt_pk_bf16_f32 v19, v22, v23
	global_store_dwordx4 v11, v[16:19], s[38:39]
	s_nop 1
	s_add_i32 s4, s56, 2368
	s_cmpk_lt_u32 s4, 0x1000
	s_cselect_b32 s34, s12, s14
	s_cselect_b32 s35, s13, s15
	s_cselect_b32 s2, 0, 0x1000
	s_sub_i32 s2, s4, s2
	s_lshl_b32 s2, s2, 14
	s_add_u32 s34, s34, s2
	s_addc_u32 s35, s35, 0
	s_lshl_b32 s2, s4, 13
	s_add_u32 s36, s0, s2
	s_addc_u32 s37, s1, 0
	global_load_dwordx4 v[0:3], v10, s[34:35]
	global_load_dwordx4 v[12:15], v10, s[34:35] offset:16
	s_add_i32 s4, s56, 2624
	s_cmpk_lt_u32 s4, 0x1000
	s_cselect_b32 s34, s12, s14
	s_cselect_b32 s35, s13, s15
	s_cselect_b32 s2, 0, 0x1000
	s_sub_i32 s2, s4, s2
	s_lshl_b32 s2, s2, 14
	s_add_u32 s34, s34, s2
	s_addc_u32 s35, s35, 0
	s_lshl_b32 s2, s4, 13
	s_add_u32 s38, s0, s2
	s_addc_u32 s39, s1, 0
	global_load_dwordx4 v[16:19], v10, s[34:35]
	global_load_dwordx4 v[20:23], v10, s[34:35] offset:16
	s_waitcnt vmcnt(6)
	v_cvt_pk_bf16_f32 v24, v24, v25
	v_cvt_pk_bf16_f32 v25, v26, v27
	v_cvt_pk_bf16_f32 v26, v244, v245
	v_cvt_pk_bf16_f32 v27, v246, v247
	global_store_dwordx4 v11, v[24:27], s[40:41]
	v_cvt_pk_bf16_f32 v248, v248, v249
	v_cvt_pk_bf16_f32 v249, v250, v251
	v_cvt_pk_bf16_f32 v250, v252, v253
	v_cvt_pk_bf16_f32 v251, v254, v255
	global_store_dwordx4 v11, v[248:251], s[42:43]
	s_nop 1
	s_waitcnt vmcnt(2)
	v_cvt_pk_bf16_f32 v0, v0, v1
	v_cvt_pk_bf16_f32 v1, v2, v3
	v_cvt_pk_bf16_f32 v2, v12, v13
	v_cvt_pk_bf16_f32 v3, v14, v15
	global_store_dwordx4 v11, v[0:3], s[36:37]
	v_cvt_pk_bf16_f32 v16, v16, v17
	v_cvt_pk_bf16_f32 v17, v18, v19
	v_cvt_pk_bf16_f32 v18, v20, v21
	v_cvt_pk_bf16_f32 v19, v22, v23
	global_store_dwordx4 v11, v[16:19], s[38:39]
	s_nop 1
	s_branch .LBB0_63
.LBB0_63:
	v_readlane_b32 s8, v241, 9
	v_readlane_b32 s9, v241, 10
	s_mul_i32 s0, s9, s8
	s_mul_i32 s0, s0, s33
	v_writelane_b32 v241, s0, 49
	s_add_u32 s0, s92, 0x37bc4200
	s_addc_u32 s1, s93, 0
	v_writelane_b32 v241, s0, 50
	v_mbcnt_lo_u32_b32 v187, -1, 0
	v_mbcnt_hi_u32_b32 v188, -1, v187
	v_writelane_b32 v241, s1, 51
	s_add_u32 s0, s92, 0x37bc4400
	s_addc_u32 s1, s93, 0
	v_writelane_b32 v241, s0, 52
	v_bfrev_b32_e32 v189, 0.5
	v_mov_b32_e32 v169, 0
	v_writelane_b32 v241, s1, 53
	s_add_u32 s0, s92, 0x37bc4500
	s_addc_u32 s1, s93, 0
	v_writelane_b32 v241, s0, 54
	v_mov_b32_e32 v179, 0x1000
	v_mov_b32_e32 v180, 0x2000
	v_writelane_b32 v241, s1, 55
	s_add_u32 s0, s92, 0x37bc4600
	s_addc_u32 s1, s93, 0
	v_writelane_b32 v241, s0, 56
	v_mov_b32_e32 v181, 1
	v_mov_b32_e32 v182, 0x155d8000
	v_writelane_b32 v241, s1, 57
	s_add_u32 s0, s92, 0x37bc4700
	s_addc_u32 s1, s93, 0
	v_writelane_b32 v241, s0, 58
	v_mov_b32_e32 v183, 0x358637bd
	v_mov_b32_e32 v184, 0x37bc0000
	v_writelane_b32 v241, s1, 59
	s_add_u32 s0, s92, 0x37bc4800
	s_addc_u32 s1, s93, 0
	v_writelane_b32 v241, s0, 60
	v_mov_b32_e32 v185, 0x3727c5ac
	v_mov_b64_e32 v[170:171], 0x3cb
	v_writelane_b32 v241, s1, 61
	s_add_u32 s0, s92, 0x37bc4900
	s_addc_u32 s1, s93, 0
	v_writelane_b32 v241, s0, 62
	v_mov_b32_e32 v186, 0x41b17218
	v_lshl_or_b32 v190, v188, 2, v189
	v_writelane_b32 v241, s1, 63
	s_add_u32 s0, s92, 0x37bc4a00
	s_addc_u32 s1, s93, 0
	v_writelane_b32 v240, s0, 0
	v_mov_b32_e32 v191, 3
	v_mov_b32_e32 v192, 0x3600
	v_writelane_b32 v240, s1, 1
	s_add_u32 s0, s92, 0x37bc4b00
	s_addc_u32 s1, s93, 0
	v_writelane_b32 v240, s0, 2
	v_mov_b64_e32 v[172:173], 0x11f
	v_mov_b64_e32 v[174:175], 0x60b
	v_writelane_b32 v240, s1, 3
	s_add_u32 s0, s92, 0x37bc4c00
	s_addc_u32 s1, s93, 0
	v_writelane_b32 v240, s0, 4
	s_movk_i32 s74, 0xfc00
	s_movk_i32 s75, 0x2000
	v_writelane_b32 v240, s1, 5
	s_add_u32 s0, s92, 0x37bc4d00
	s_addc_u32 s1, s93, 0
	v_writelane_b32 v240, s0, 6
	s_movk_i32 s33, 0x4000
	s_movk_i32 s52, 0x60
	v_writelane_b32 v240, s1, 7
	s_add_u32 s0, s92, 0x37bc4e00
	s_addc_u32 s1, s93, 0
	v_writelane_b32 v240, s0, 8
	s_movk_i32 s54, 0x3600
	s_mov_b32 s59, 0xbfb8aa3b
	v_writelane_b32 v240, s1, 9
	s_add_u32 s0, s92, 0x37bc4f00
	s_addc_u32 s1, s93, 0
	v_writelane_b32 v240, s0, 10
	s_mov_b32 s60, 0x800000
	s_mov_b32 s61, 0x3f317217
	v_writelane_b32 v240, s1, 11
	s_add_u32 s0, s92, 0x37bc5000
	s_addc_u32 s1, s93, 0
	v_writelane_b32 v240, s0, 12
	s_mov_b32 s62, 0x7f800000
	s_movk_i32 s63, 0x1000
	v_writelane_b32 v240, s1, 13
	s_add_u32 s0, s92, 0x37bc5100
	s_addc_u32 s1, s93, 0
	v_writelane_b32 v240, s0, 14
	s_movk_i32 s64, 0x220
	s_movk_i32 s66, 0xc00
	v_writelane_b32 v240, s1, 15
	s_add_u32 s0, s92, 0x37bc5200
	s_addc_u32 s1, s93, 0
	v_writelane_b32 v240, s0, 16
	s_mov_b32 s67, 0x2aaaaaab
	s_movk_i32 s55, 0x4f
	v_writelane_b32 v240, s1, 17
	s_add_u32 s0, s92, 0x37bc5300
	s_addc_u32 s1, s93, 0
	v_writelane_b32 v240, s0, 18
	s_movk_i32 s65, 0x420
	s_mov_b32 s31, 0
	v_writelane_b32 v240, s1, 19
	s_add_u32 s0, s92, 0x37bc7400
	s_addc_u32 s1, s93, 0
	v_writelane_b32 v240, s0, 20
	s_mov_b64 s[34:35], 0x1800
	s_mov_b64 s[76:77], 0x4800
	v_writelane_b32 v240, s1, 21
	s_add_u32 s0, s92, 0x37bc7500
	s_addc_u32 s1, s93, 0
	v_writelane_b32 v240, s0, 22
	s_nop 1
	v_writelane_b32 v240, s1, 23
	s_add_u32 s0, s92, 0xc700000
	s_addc_u32 s1, s93, 0
	s_add_u32 s80, s92, 0x13300000
	v_writelane_b32 v240, s0, 24
	s_addc_u32 s81, s93, 0
	s_nop 0
	v_writelane_b32 v240, s1, 25
	s_add_u32 s0, s92, 0x37bc0000
	s_addc_u32 s1, s93, 0
	v_writelane_b32 v240, s0, 26
	s_nop 1
	v_writelane_b32 v240, s1, 27
	s_add_u32 s0, s92, 0x37ac0000
	v_writelane_b32 v240, s0, 28
	s_addc_u32 s0, s93, 0
	s_add_u32 s94, s92, 0x21880000
	s_addc_u32 s95, s93, 0
	v_writelane_b32 v240, s0, 29
	s_add_u32 s0, s92, 0x37bc2000
	s_addc_u32 s1, s93, 0
	v_writelane_b32 v240, s0, 30
	s_nop 1
	v_writelane_b32 v240, s1, 31
	s_add_u32 s0, s92, 0xeb00000
	v_writelane_b32 v240, s0, 32
	s_addc_u32 s0, s93, 0
	v_writelane_b32 v240, s0, 33
	s_add_u32 s0, s92, 0x29880000
	s_addc_u32 s1, s93, 0
	v_writelane_b32 v240, s0, 34
	s_nop 1
	v_writelane_b32 v240, s1, 35
	v_readlane_b32 s0, v241, 1
	v_readlane_b32 s6, v241, 7
	v_readlane_b32 s7, v241, 8
	s_add_u32 s0, s6, 0x54d8080
	v_writelane_b32 v240, s0, 36
	s_addc_u32 s0, s7, 0
	v_readlane_b32 s1, v241, 2
	v_writelane_b32 v240, s0, 37
	s_add_u32 s0, s92, 0x1ac80000
	s_addc_u32 s1, s93, 0
	v_writelane_b32 v240, s0, 38
	v_readlane_b32 s2, v241, 3
	v_readlane_b32 s3, v241, 4
	v_writelane_b32 v240, s1, 39
	s_add_u32 s0, s6, 0x155d9080
	s_addc_u32 s1, s7, 0
	v_writelane_b32 v240, s0, 40
	v_readlane_b32 s4, v241, 5
	v_readlane_b32 s5, v241, 6
	v_writelane_b32 v240, s1, 41
	s_add_u32 s0, s92, 0x1ac80800
	s_addc_u32 s1, s93, 0
	v_writelane_b32 v240, s0, 42
	s_nop 1
	v_writelane_b32 v240, s1, 43
	s_add_u32 s0, s92, 0x37bc1000
	v_writelane_b32 v240, s0, 44
	s_addc_u32 s0, s93, 0
	v_writelane_b32 v240, s0, 45
	s_add_u32 s0, s92, 0x2da00000
	s_addc_u32 s1, s93, 0
	v_writelane_b32 v240, s0, 46
	s_nop 1
	v_writelane_b32 v240, s1, 47
	s_add_u32 s0, s6, 0x4800000
	v_writelane_b32 v240, s0, 48
	s_addc_u32 s0, s7, 0
	v_writelane_b32 v240, s0, 49
	s_add_u32 s0, s92, 0x37b40000
	v_writelane_b32 v240, s0, 50
	s_addc_u32 s0, s93, 0
	v_writelane_b32 v240, s0, 51
	s_add_u32 s0, s6, 0x5008080
	v_writelane_b32 v240, s0, 52
	s_addc_u32 s0, s7, 0
	v_writelane_b32 v240, s0, 53
	s_add_u32 s0, s92, 0x31a00000
	s_addc_u32 s1, s93, 0
	v_writelane_b32 v240, s0, 54
	s_nop 1
	v_writelane_b32 v240, s1, 55
	s_add_u32 s0, s92, 0x9c00000
	v_writelane_b32 v240, s0, 56
	s_addc_u32 s0, s93, 0
	v_writelane_b32 v240, s0, 57
	s_add_u32 s0, s92, 0x4600000
	v_writelane_b32 v240, s0, 58
	s_addc_u32 s0, s93, 0
	v_writelane_b32 v240, s0, 59
	s_add_u32 s0, s92, 0x3600000
	v_writelane_b32 v240, s0, 60
	s_addc_u32 s0, s93, 0
	v_writelane_b32 v240, s0, 61
	s_add_u32 s0, s92, 0x1d080000
	s_addc_u32 s1, s93, 0
	v_writelane_b32 v240, s0, 62
	s_nop 1
	v_writelane_b32 v240, s1, 63
	s_add_u32 s0, s92, 0x33ac0000
	s_addc_u32 s1, s93, 0
	v_writelane_b32 v239, s0, 0
	s_nop 1
	v_writelane_b32 v239, s1, 1
	v_readlane_b32 s0, v241, 0
	s_lshl_b32 s0, s0, 3
	s_nop 0
	v_writelane_b32 v239, s0, 2
	s_lshl_b32 s0, s8, 3
	v_writelane_b32 v239, s0, 3
	s_add_u32 s0, s6, 0x1da59080
	s_addc_u32 s1, s7, 0
	v_writelane_b32 v239, s0, 4
	s_nop 1
	v_writelane_b32 v239, s1, 5
	s_add_u32 s0, s6, 0x542c080
	s_addc_u32 s1, s7, 0
	v_writelane_b32 v239, s0, 6
	s_nop 1
	v_writelane_b32 v239, s1, 7
	s_add_u32 s0, s92, 0x7100000
	v_writelane_b32 v239, s0, 8
	s_addc_u32 s0, s93, 0
	v_writelane_b32 v239, s0, 9
	v_readlane_b32 s0, v241, 27
	v_readlane_b32 s12, v241, 39
	v_readlane_b32 s1, v241, 28
	v_readlane_b32 s13, v241, 40
	s_add_u32 s0, s12, 0x20400
	s_addc_u32 s1, s13, 0
	v_readlane_b32 s14, v241, 41
	v_writelane_b32 v239, s0, 10
	v_readlane_b32 s15, v241, 42
	v_readlane_b32 s10, v241, 37
	v_writelane_b32 v239, s1, 11
	s_add_u32 s0, s14, 0xac00
	s_addc_u32 s1, s15, 0
	v_writelane_b32 v239, s0, 12
	v_readlane_b32 s11, v241, 38
	s_mov_b64 s[10:11], 0x3000
	v_writelane_b32 v239, s1, 13
	s_add_u32 s0, s14, 0x10200
	s_addc_u32 s1, s15, 0
	v_writelane_b32 v239, s0, 14
	v_readlane_b32 s2, v241, 29
	v_readlane_b32 s3, v241, 30
	v_writelane_b32 v239, s1, 15
	s_add_u32 s0, s12, 0x25a00
	s_addc_u32 s1, s13, 0
	v_writelane_b32 v239, s0, 16
	v_readlane_b32 s4, v241, 31
	v_readlane_b32 s5, v241, 32
	v_writelane_b32 v239, s1, 17
	s_add_u32 s0, s12, 0x2b000
	s_addc_u32 s1, s13, 0
	v_writelane_b32 v239, s0, 18
	v_readlane_b32 s6, v241, 33
	v_readlane_b32 s7, v241, 34
	v_writelane_b32 v239, s1, 19
	s_add_u32 s0, s12, 0x30600
	s_addc_u32 s1, s13, 0
	v_writelane_b32 v239, s0, 20
	v_readlane_b32 s8, v241, 35
	v_readlane_b32 s9, v241, 36
	v_writelane_b32 v239, s1, 21
	s_add_u32 s0, s12, 0x35c00
	s_addc_u32 s1, s13, 0
	v_writelane_b32 v239, s0, 22
	s_nop 1
	v_writelane_b32 v239, s1, 23
	s_add_u32 s0, s12, 0x3b200
	s_addc_u32 s1, s13, 0
	v_writelane_b32 v239, s0, 24
	s_nop 1
	v_writelane_b32 v239, s1, 25
	s_add_u32 s0, s92, 0x2dae0000
	v_writelane_b32 v239, s0, 26
	s_addc_u32 s0, s93, 0
	v_writelane_b32 v239, s0, 27
	s_add_u32 s0, s92, 0x31a1c000
	v_writelane_b32 v239, s0, 28
	s_addc_u32 s0, s93, 0
	v_writelane_b32 v239, s0, 29
	s_add_i32 s0, 0, 0x21ff0
	v_writelane_b32 v239, s0, 30
	s_add_i32 s0, 0, 0x21ff4
	v_writelane_b32 v239, s0, 31
	s_add_i32 s0, 0, 0xa680
	v_writelane_b32 v239, s0, 32
	s_add_i32 s0, 0, 0x19000
	v_writelane_b32 v239, s0, 33
	s_add_i32 s0, 0, 0x1c600
	v_writelane_b32 v239, s0, 34
	s_add_i32 s0, 0, 0x14c00
	v_writelane_b32 v239, s0, 35
	s_add_i32 s0, 0, 0x1e400
	v_writelane_b32 v239, s0, 36
	s_mov_b32 s0, 0
	v_writelane_b32 v239, s0, 37
	s_mov_b64 s[0:1], 0
	v_writelane_b32 v239, s0, 38
	s_add_i32 s53, 0, 0x10800
	s_nop 0
	v_writelane_b32 v239, s1, 39
	s_mov_b64 s[0:1], -1
	v_writelane_b32 v239, s0, 40
	s_nop 1
	v_writelane_b32 v239, s1, 41
	v_writelane_b32 v239, s92, 42
	s_mov_b64 s[0:1], 0x80
	s_nop 0
	v_writelane_b32 v239, s93, 43
	v_writelane_b32 v239, s94, 44
	s_nop 1
	v_writelane_b32 v239, s95, 45
	s_branch .LBB0_65
